# nt hint on HGRN's read-once projection-row loads as well (on v73)
# speedup vs baseline: 1.0004x; 1.0004x over previous
; __device__ __forceinline__ int lane_id_() { int l; asm volatile("v_mbcnt_lo_u32_b32 %0, -1, 0\n\tv_mbcnt_hi_u32_b32 %0, -1, %0" : "=v"(l)); return l; }
; __device__ __forceinline__ void hgrn_chunked_bh(const Ctx& F, int b, int h) {
;     ...
;     const int lane = lane_id_(), w = F.wid, tid = w * 64 + lane, c16 = lane & 15, g = lane >> 4;
;     const int pt = lane & 31, phalf = lane >> 5, k0 = 16 * w + 8 * phalf;
;     float lb8[8];
;     { const f32x4 l0 = *(const f32x4*)(lb + h * 128 + k0), l1 = *(const f32x4*)(lb + h * 128 + k0 + 4); lb8[0] = l0[0]; lb8[1] = l0[1]; lb8[2] = l0[2]; lb8[3] = l0[3]; lb8[4] = l1[0]; lb8[5] = l1[1]; lb8[6] = l1[2]; lb8[7] = l1[3]; }
;     const float gn0 = F_hg_norm[lane], gn1 = F_hg_norm[64 + lane];
;     f32x4 st[8];
; #pragma unroll
;     for (int i = 0; i < 8; ++i) st[i] = (f32x4){0.f, 0.f, 0.f, 0.f};
;     u32x4 rq, rf, rv;
;     { const bf16_t* p = proj + ((size_t)b * S + pt) * IN_ODD + h * 128 + k0; rq = *(const u32x4*)p; rf = *(const u32x4*)(p + 1024); rv = *(const u32x4*)(p + 2048); }
;     bf16_t gqp[4][2] = {};
;     ...
;         bf16_t gq[4][2];
; #pragma unroll
;         for (int i = 0; i < 4; ++i) { const bf16_t* gp = proj + ((size_t)b * S + 32 * c + w + 8 * i) * IN_ODD + 3072 + h * 128; gq[i][0] = gp[lane]; gq[i][1] = gp[64 + lane]; }
.LBB0_1377:
	s_lshl_b32 s4, s69, 1
	s_and_b32 s42, s4, 0x700
	s_lshl_b32 s4, s79, 7
	s_and_b32 s18, s4, 0x380
	v_mbcnt_lo_u32_b32 v20, -1, 0
	v_mbcnt_hi_u32_b32 v20, -1, v20
	v_and_b32_e32 v172, 15, v20
	v_and_b32_e32 v173, 16, v20
	v_lshl_add_u32 v172, s50, 4, v172
	v_lshlrev_b32_e32 v172, 2, v172
	v_lshl_add_u32 v172, v173, 5, v172
	s_ashr_i32 s40, s79, 3
	s_waitcnt lgkmcnt(0)
	v_ashrrev_i32_e32 v0, 2, v20
	s_lshl_b32 s4, s18, 2
	v_and_b32_e32 v22, -8, v0
	s_add_u32 s4, s0, s4
	v_add_u32_e32 v102, s3, v22
	s_addc_u32 s5, s1, 0
	v_ashrrev_i32_e32 v103, 31, v102
	v_lshl_add_u64 v[8:9], v[102:103], 2, s[4:5]
	global_load_dwordx4 v[0:3], v[8:9], off nt
	global_load_dwordx4 v[4:7], v[8:9], off offset:16 nt
	s_load_dwordx2 s[16:17], s[56:57], 0xd0
	v_ashrrev_i32_e32 v8, 4, v20
	v_and_b32_e32 v23, 15, v20
	v_ashrrev_i32_e32 v21, 31, v20
	v_lshlrev_b32_e32 v120, 3, v8
	v_lshlrev_b32_e32 v25, 2, v8
	v_or_b32_e32 v8, s3, v23
	s_ashr_i32 s41, s40, 31
	v_and_b32_e32 v24, 31, v20
	v_mul_lo_u32 v122, v8, s72
	s_lshl_b32 s52, s18, 1
	s_lshl_b64 s[60:61], s[40:41], 11
	s_waitcnt lgkmcnt(0)
	v_lshl_add_u64 v[8:9], v[20:21], 2, s[16:17]
	v_readlane_b32 s16, v254, 4
	v_readlane_b32 s17, v254, 5
	s_add_u32 s16, s16, s52
	flat_load_dword v115, v[8:9]
	flat_load_dword v114, v[8:9] offset:256
	v_or_b32_e32 v8, s60, v24
	v_mov_b32_e32 v9, s61
	s_addc_u32 s17, s17, 0
	v_lshlrev_b64 v[8:9], 13, v[8:9]
	v_lshl_add_u64 v[8:9], s[16:17], 0, v[8:9]
	v_lshl_add_u64 v[16:17], v[102:103], 1, v[8:9]
	v_add_co_u32_e32 v188, vcc, 0x40000, v16
	s_nop 1
	v_addc_co_u32_e32 v189, vcc, 0, v17, vcc
	v_add_co_u32_e32 v190, vcc, 0x41000, v16
	s_nop 1
	v_addc_co_u32_e32 v191, vcc, 0, v17, vcc
	global_load_dwordx4 v[176:179], v[188:189], off nt
	global_load_dwordx4 v[180:183], v[188:189], off offset:2048 nt
	global_load_dwordx4 v[184:187], v[190:191], off nt
	global_load_dwordx4 v[8:11], v[16:17], off nt
	global_load_dwordx4 v[12:15], v[16:17], off offset:2048 nt
	v_add_co_u32_e32 v16, vcc, s71, v16
	v_readlane_b32 s53, v254, 0
	s_nop 0
	v_addc_co_u32_e32 v17, vcc, 0, v17, vcc
	global_load_dwordx4 v[16:19], v[16:17], off nt
	s_add_u32 s62, s53, s52
	v_readlane_b32 s52, v254, 1
	v_or_b32_e32 v26, 16, v23
	s_addc_u32 s63, s52, 0
	s_lshl_b64 s[40:41], s[40:41], 24
	v_add_u32_e32 v27, 16, v25
	v_cmp_gt_i32_e64 s[8:9], v25, v23
	v_cmp_lt_i32_e64 s[10:11], v25, v23
	v_or_b32_e32 v28, 2, v25
	v_or_b32_e32 v29, 3, v25
	v_cmp_gt_i32_e64 s[12:13], v25, v26
	v_cmp_lt_i32_e64 s[14:15], v25, v26
	v_add_u32_e32 v30, 17, v25
	v_add_u32_e32 v31, 18, v25
	v_add_u32_e32 v25, 19, v25
	s_or_b32 s40, s40, s42
	v_and_b32_e32 v117, -16, v20
	v_lshlrev_b32_e32 v116, 2, v20
	v_mul_u32_u24_e32 v121, 0x110, v23
	v_cmp_gt_i32_e64 s[16:17], v28, v23
	v_cmp_gt_i32_e64 s[18:19], v29, v23
	v_cmp_gt_i32_e64 s[24:25], v27, v23
	v_cmp_gt_i32_e64 s[26:27], v30, v23
	v_cmp_gt_i32_e64 s[28:29], v31, v23
	v_cmp_gt_i32_e64 s[30:31], v25, v23
	v_mul_u32_u24_e32 v133, 0x50, v23
	v_mul_u32_u24_e32 v134, 0x210, v23
	s_waitcnt vmcnt(0)
	v_lshlrev_b64 v[100:101], 1, v[20:21]
	v_lshl_or_b32 v20, v24, 13, s40
	v_mov_b32_e32 v21, s41
	v_ashrrev_i32_e32 v23, 31, v22
	s_add_u32 s64, s55, s40
	v_lshl_add_u64 v[20:21], v[22:23], 1, v[20:21]
	s_addc_u32 s65, s68, s41
	v_lshl_add_u64 v[108:109], s[58:59], 0, v[20:21]
	v_mov_b32_e32 v20, 0
	v_cmp_eq_u32_e64 s[4:5], 15, v24
	v_cmp_eq_u32_e64 s[6:7], 31, v24
	v_mul_u32_u24_e32 v118, 0x110, v24
	v_lshlrev_b32_e32 v119, 1, v24
	v_lshlrev_b32_e32 v103, 1, v102
	v_mul_lo_u32 v123, v102, s72
	v_cmp_gt_i32_e64 s[20:21], v28, v26
	v_cmp_gt_i32_e64 s[22:23], v29, v26
	v_cmp_gt_i32_e64 s[34:35], v30, v26
	v_cmp_gt_i32_e64 s[36:37], v31, v26
	v_cmp_gt_i32_e64 s[38:39], v25, v26
	v_lshlrev_b32_e32 v124, 2, v27
	v_sub_f32_e32 v125, 1.0, v0
	v_sub_f32_e32 v126, 1.0, v1
	v_sub_f32_e32 v127, 1.0, v2
	v_sub_f32_e32 v128, 1.0, v3
	v_sub_f32_e32 v129, 1.0, v4
	v_sub_f32_e32 v130, 1.0, v5
	v_sub_f32_e32 v131, 1.0, v6
	v_sub_f32_e32 v132, 1.0, v7
	v_add_u32_e32 v135, 0, v116
	v_lshl_add_u64 v[104:105], s[62:63], 0, v[100:101]
	v_lshl_add_u64 v[106:107], s[64:65], 0, v[100:101]
	s_movk_i32 s42, 0xffe0
	s_mov_b64 s[64:65], 0
	s_mov_b32 s66, -1
	v_mov_b32_e32 v21, v20
	v_mov_b32_e32 v22, v20
	v_mov_b32_e32 v23, v20
	v_mov_b32_e32 v24, v20
	v_mov_b32_e32 v25, v20
	v_mov_b32_e32 v26, v20
	v_mov_b32_e32 v27, v20
	v_mov_b32_e32 v28, v20
	v_mov_b32_e32 v29, v20
	v_mov_b32_e32 v30, v20
	v_mov_b32_e32 v31, v20
	v_mov_b32_e32 v32, v20
	v_mov_b32_e32 v33, v20
	v_mov_b32_e32 v34, v20
	v_mov_b32_e32 v35, v20
	v_mov_b32_e32 v36, v20
	v_mov_b32_e32 v37, v20
	v_mov_b32_e32 v38, v20
	v_mov_b32_e32 v39, v20
	v_mov_b32_e32 v40, v20
	v_mov_b32_e32 v41, v20
	v_mov_b32_e32 v42, v20
	v_mov_b32_e32 v43, v20
	v_mov_b32_e32 v44, v20
	v_mov_b32_e32 v45, v20
	v_mov_b32_e32 v46, v20
	v_mov_b32_e32 v47, v20
	v_mov_b32_e32 v48, v20
	v_mov_b32_e32 v49, v20
	v_mov_b32_e32 v50, v20
	v_mov_b32_e32 v51, v20
	v_mov_b32_e32 v139, 0
	v_mov_b32_e32 v138, 0
	v_mov_b32_e32 v137, 0
	v_mov_b32_e32 v136, 0
	s_branch .LBB0_1379
.LBB0_1378:
	v_lshl_add_u64 v[52:53], v[106:107], 0, s[64:65]
	v_add_co_u32_e32 v54, vcc, 0xc201000, v52
	s_nop 1
	v_addc_co_u32_e32 v55, vcc, 0, v53, vcc
	v_add_co_u32_e32 v56, vcc, 0xc211000, v52
	s_nop 1
	v_addc_co_u32_e32 v57, vcc, 0, v53, vcc
	v_add_co_u32_e32 v58, vcc, 0xc221000, v52
	s_nop 1
	v_addc_co_u32_e32 v59, vcc, 0, v53, vcc
	v_add_co_u32_e32 v52, vcc, 0xc231000, v52
	s_nop 1
	v_addc_co_u32_e32 v53, vcc, 0, v53, vcc
	global_load_ushort v146, v[54:55], off offset:2048 nt
	global_load_ushort v147, v[54:55], off offset:2176 nt
	global_load_ushort v143, v[56:57], off offset:2048 nt
	global_load_ushort v144, v[56:57], off offset:2176 nt
	global_load_ushort v145, v[58:59], off offset:2048 nt
	global_load_ushort v140, v[58:59], off offset:2176 nt
	global_load_ushort v141, v[52:53], off offset:2048 nt
	global_load_ushort v142, v[52:53], off offset:2176 nt
	s_add_i32 s42, s42, 32
	s_add_u32 s64, s64, 0x40000
	s_addc_u32 s65, s65, 0
	s_cmp_lg_u32 s64, 0x1000000
	s_mov_b32 s66, s80
	s_cbranch_scc0 .LBB0_1376

; __device__ __forceinline__ void hgrn_chunked_bh(const Ctx& F, int b, int h) {
;     ...
;         if (c + 1 < S / 32) { const bf16_t* p = proj + ((size_t)b * S + 32 * (c + 1) + pt) * IN_ODD + h * 128 + k0; rq = *(const u32x4*)p; rf = *(const u32x4*)(p + 1024); rv = *(const u32x4*)(p + 2048); }
.LBB0_1394:
	v_add_u32_e32 v162, s67, v120
	v_add_u32_e32 v152, v162, v121
	v_add_u32_e32 v148, 0x2000, v152
	v_add_u32_e32 v156, 0x1000, v152
	s_cmp_lt_u32 s64, 0xf80000
	s_cbranch_scc0 .Lhg_nopf
	v_lshl_add_u64 v[188:189], v[108:109], 0, s[64:65]
	v_add_co_u32_e32 v190, vcc, 0xc280000, v188
	s_nop 1
	v_addc_co_u32_e32 v191, vcc, 0, v189, vcc
	v_add_co_u32_e32 v188, vcc, 0xc281000, v188
	s_nop 1
	v_addc_co_u32_e32 v189, vcc, 0, v189, vcc
	global_load_dwordx4 v[176:179], v[190:191], off nt
	global_load_dwordx4 v[180:183], v[190:191], off offset:2048 nt
	global_load_dwordx4 v[184:187], v[188:189], off nt
